# v2 + packed SwiGLU epilogue, two 4-element groups interleaved with separate temps (8 independent exp/rcp in flight)
# baseline (speedup 1.0000x reference)
.LBB0_163:
	v_mov_b32_e32 v164, 0xbfb8aa3b
	s_lshl_b32 s5, s42, 7
	s_or_b32 s5, s5, s36
	s_mul_i32 s14, s41, 0x2c0000
	s_mul_hi_i32 s7, s41, 0x2c0000
	s_add_u32 s16, s34, s14
	s_addc_u32 s7, s35, s7
	s_ashr_i32 s14, s5, 6
	s_ashr_i32 s15, s14, 31
	s_lshl_b64 s[14:15], s[14:15], 15
	s_add_u32 s14, s16, s14
	s_addc_u32 s15, s7, s15
	v_lshl_add_u64 v[154:155], s[14:15], 0, v[2:3]
	v_lshl_add_u64 v[156:157], v[140:141], 1, v[154:155]
	s_mov_b64 s[14:15], -1
	s_movk_i32 s45, 0x3000
	s_mov_b32 s47, 0x11000
	s_mov_b32 s48, 0x9000
	v_pk_mul_f32 v[160:161], v[128:129], v[164:165] op_sel_hi:[1,0]
	v_pk_mul_f32 v[162:163], v[130:131], v[164:165] op_sel_hi:[1,0]
	v_pk_mul_f32 v[166:167], v[120:121], v[164:165] op_sel_hi:[1,0]
	v_pk_mul_f32 v[168:169], v[122:123], v[164:165] op_sel_hi:[1,0]
	v_exp_f32_e32 v160, v160
	v_exp_f32_e32 v161, v161
	v_exp_f32_e32 v162, v162
	v_exp_f32_e32 v163, v163
	v_exp_f32_e32 v166, v166
	v_exp_f32_e32 v167, v167
	v_exp_f32_e32 v168, v168
	v_exp_f32_e32 v169, v169
	v_pk_add_f32 v[160:161], v[160:161], 1.0 op_sel_hi:[1,0]
	v_pk_add_f32 v[162:163], v[162:163], 1.0 op_sel_hi:[1,0]
	v_pk_add_f32 v[166:167], v[166:167], 1.0 op_sel_hi:[1,0]
	v_pk_add_f32 v[168:169], v[168:169], 1.0 op_sel_hi:[1,0]
	v_rcp_f32_e32 v160, v160
	v_rcp_f32_e32 v161, v161
	v_rcp_f32_e32 v162, v162
	v_rcp_f32_e32 v163, v163
	v_rcp_f32_e32 v166, v166
	v_rcp_f32_e32 v167, v167
	v_rcp_f32_e32 v168, v168
	v_rcp_f32_e32 v169, v169
	v_pk_mul_f32 v[160:161], v[128:129], v[160:161]
	v_pk_mul_f32 v[162:163], v[130:131], v[162:163]
	v_pk_mul_f32 v[166:167], v[120:121], v[166:167]
	v_pk_mul_f32 v[168:169], v[122:123], v[168:169]
	v_pk_mul_f32 v[160:161], v[160:161], v[124:125]
	v_pk_mul_f32 v[162:163], v[162:163], v[126:127]
	v_pk_mul_f32 v[166:167], v[166:167], v[116:117]
	v_pk_mul_f32 v[168:169], v[168:169], v[118:119]
	v_cvt_pk_bf16_f32 v124, v160, v161
	v_cvt_pk_bf16_f32 v125, v162, v163
	v_cvt_pk_bf16_f32 v126, v166, v167
	v_cvt_pk_bf16_f32 v127, v168, v169
	global_store_dwordx4 v[156:157], v[124:127], off nt
	v_pk_mul_f32 v[160:161], v[112:113], v[164:165] op_sel_hi:[1,0]
	v_pk_mul_f32 v[162:163], v[114:115], v[164:165] op_sel_hi:[1,0]
	v_pk_mul_f32 v[166:167], v[104:105], v[164:165] op_sel_hi:[1,0]
	v_pk_mul_f32 v[168:169], v[106:107], v[164:165] op_sel_hi:[1,0]
	v_exp_f32_e32 v160, v160
	v_exp_f32_e32 v161, v161
	v_exp_f32_e32 v162, v162
	v_exp_f32_e32 v163, v163
	v_exp_f32_e32 v166, v166
	v_exp_f32_e32 v167, v167
	v_exp_f32_e32 v168, v168
	v_exp_f32_e32 v169, v169
	v_pk_add_f32 v[160:161], v[160:161], 1.0 op_sel_hi:[1,0]
	v_pk_add_f32 v[162:163], v[162:163], 1.0 op_sel_hi:[1,0]
	v_pk_add_f32 v[166:167], v[166:167], 1.0 op_sel_hi:[1,0]
	v_pk_add_f32 v[168:169], v[168:169], 1.0 op_sel_hi:[1,0]
	v_rcp_f32_e32 v160, v160
	v_rcp_f32_e32 v161, v161
	v_rcp_f32_e32 v162, v162
	v_rcp_f32_e32 v163, v163
	v_rcp_f32_e32 v166, v166
	v_rcp_f32_e32 v167, v167
	v_rcp_f32_e32 v168, v168
	v_rcp_f32_e32 v169, v169
	v_pk_mul_f32 v[160:161], v[112:113], v[160:161]
	v_pk_mul_f32 v[162:163], v[114:115], v[162:163]
	v_pk_mul_f32 v[166:167], v[104:105], v[166:167]
	v_pk_mul_f32 v[168:169], v[106:107], v[168:169]
	v_pk_mul_f32 v[160:161], v[160:161], v[108:109]
	v_pk_mul_f32 v[162:163], v[162:163], v[110:111]
	v_pk_mul_f32 v[166:167], v[166:167], v[100:101]
	v_pk_mul_f32 v[168:169], v[168:169], v[102:103]
	v_cvt_pk_bf16_f32 v108, v160, v161
	v_cvt_pk_bf16_f32 v109, v162, v163
	v_cvt_pk_bf16_f32 v110, v166, v167
	v_cvt_pk_bf16_f32 v111, v168, v169
	global_store_dwordx4 v[156:157], v[108:111], off offset:2048 nt
	v_pk_mul_f32 v[160:161], v[96:97], v[164:165] op_sel_hi:[1,0]
	v_pk_mul_f32 v[162:163], v[98:99], v[164:165] op_sel_hi:[1,0]
	v_pk_mul_f32 v[166:167], v[88:89], v[164:165] op_sel_hi:[1,0]
	v_pk_mul_f32 v[168:169], v[90:91], v[164:165] op_sel_hi:[1,0]
	v_exp_f32_e32 v160, v160
	v_exp_f32_e32 v161, v161
	v_exp_f32_e32 v162, v162
	v_exp_f32_e32 v163, v163
	v_exp_f32_e32 v166, v166
	v_exp_f32_e32 v167, v167
	v_exp_f32_e32 v168, v168
	v_exp_f32_e32 v169, v169
	v_pk_add_f32 v[160:161], v[160:161], 1.0 op_sel_hi:[1,0]
	v_pk_add_f32 v[162:163], v[162:163], 1.0 op_sel_hi:[1,0]
	v_pk_add_f32 v[166:167], v[166:167], 1.0 op_sel_hi:[1,0]
	v_pk_add_f32 v[168:169], v[168:169], 1.0 op_sel_hi:[1,0]
	v_rcp_f32_e32 v160, v160
	v_rcp_f32_e32 v161, v161
	v_rcp_f32_e32 v162, v162
	v_rcp_f32_e32 v163, v163
	v_rcp_f32_e32 v166, v166
	v_rcp_f32_e32 v167, v167
	v_rcp_f32_e32 v168, v168
	v_rcp_f32_e32 v169, v169
	v_pk_mul_f32 v[160:161], v[96:97], v[160:161]
	v_pk_mul_f32 v[162:163], v[98:99], v[162:163]
	v_pk_mul_f32 v[166:167], v[88:89], v[166:167]
	v_pk_mul_f32 v[168:169], v[90:91], v[168:169]
	v_pk_mul_f32 v[160:161], v[160:161], v[92:93]
	v_pk_mul_f32 v[162:163], v[162:163], v[94:95]
	v_pk_mul_f32 v[166:167], v[166:167], v[84:85]
	v_pk_mul_f32 v[168:169], v[168:169], v[86:87]
	v_cvt_pk_bf16_f32 v92, v160, v161
	v_cvt_pk_bf16_f32 v93, v162, v163
	v_cvt_pk_bf16_f32 v94, v166, v167
	v_cvt_pk_bf16_f32 v95, v168, v169
	v_add_co_u32_e32 v84, vcc, s51, v156
	s_nop 1
	v_addc_co_u32_e32 v85, vcc, 0, v157, vcc
	global_store_dwordx4 v[84:85], v[92:95], off nt
	s_andn2_b64 vcc, exec, s[8:9]
	v_pk_mul_f32 v[160:161], v[80:81], v[164:165] op_sel_hi:[1,0]
	v_pk_mul_f32 v[162:163], v[82:83], v[164:165] op_sel_hi:[1,0]
	v_pk_mul_f32 v[166:167], v[72:73], v[164:165] op_sel_hi:[1,0]
	v_pk_mul_f32 v[168:169], v[74:75], v[164:165] op_sel_hi:[1,0]
	v_exp_f32_e32 v160, v160
	v_exp_f32_e32 v161, v161
	v_exp_f32_e32 v162, v162
	v_exp_f32_e32 v163, v163
	v_exp_f32_e32 v166, v166
	v_exp_f32_e32 v167, v167
	v_exp_f32_e32 v168, v168
	v_exp_f32_e32 v169, v169
	v_pk_add_f32 v[160:161], v[160:161], 1.0 op_sel_hi:[1,0]
	v_pk_add_f32 v[162:163], v[162:163], 1.0 op_sel_hi:[1,0]
	v_pk_add_f32 v[166:167], v[166:167], 1.0 op_sel_hi:[1,0]
	v_pk_add_f32 v[168:169], v[168:169], 1.0 op_sel_hi:[1,0]
	v_rcp_f32_e32 v160, v160
	v_rcp_f32_e32 v161, v161
	v_rcp_f32_e32 v162, v162
	v_rcp_f32_e32 v163, v163
	v_rcp_f32_e32 v166, v166
	v_rcp_f32_e32 v167, v167
	v_rcp_f32_e32 v168, v168
	v_rcp_f32_e32 v169, v169
	v_pk_mul_f32 v[160:161], v[80:81], v[160:161]
	v_pk_mul_f32 v[162:163], v[82:83], v[162:163]
	v_pk_mul_f32 v[166:167], v[72:73], v[166:167]
	v_pk_mul_f32 v[168:169], v[74:75], v[168:169]
	v_pk_mul_f32 v[160:161], v[160:161], v[76:77]
	v_pk_mul_f32 v[162:163], v[162:163], v[78:79]
	v_pk_mul_f32 v[166:167], v[166:167], v[68:69]
	v_pk_mul_f32 v[168:169], v[168:169], v[70:71]
	v_cvt_pk_bf16_f32 v76, v160, v161
	v_cvt_pk_bf16_f32 v77, v162, v163
	v_cvt_pk_bf16_f32 v78, v166, v167
	v_cvt_pk_bf16_f32 v79, v168, v169
	global_store_dwordx4 v[84:85], v[76:79], off offset:2048 nt
	v_lshl_add_u64 v[68:69], v[142:143], 1, v[154:155]
	v_pk_mul_f32 v[160:161], v[64:65], v[164:165] op_sel_hi:[1,0]
	v_pk_mul_f32 v[162:163], v[66:67], v[164:165] op_sel_hi:[1,0]
	v_pk_mul_f32 v[166:167], v[56:57], v[164:165] op_sel_hi:[1,0]
	v_pk_mul_f32 v[168:169], v[58:59], v[164:165] op_sel_hi:[1,0]
	v_exp_f32_e32 v160, v160
	v_exp_f32_e32 v161, v161
	v_exp_f32_e32 v162, v162
	v_exp_f32_e32 v163, v163
	v_exp_f32_e32 v166, v166
	v_exp_f32_e32 v167, v167
	v_exp_f32_e32 v168, v168
	v_exp_f32_e32 v169, v169
	v_pk_add_f32 v[160:161], v[160:161], 1.0 op_sel_hi:[1,0]
	v_pk_add_f32 v[162:163], v[162:163], 1.0 op_sel_hi:[1,0]
	v_pk_add_f32 v[166:167], v[166:167], 1.0 op_sel_hi:[1,0]
	v_pk_add_f32 v[168:169], v[168:169], 1.0 op_sel_hi:[1,0]
	v_rcp_f32_e32 v160, v160
	v_rcp_f32_e32 v161, v161
	v_rcp_f32_e32 v162, v162
	v_rcp_f32_e32 v163, v163
	v_rcp_f32_e32 v166, v166
	v_rcp_f32_e32 v167, v167
	v_rcp_f32_e32 v168, v168
	v_rcp_f32_e32 v169, v169
	v_pk_mul_f32 v[160:161], v[64:65], v[160:161]
	v_pk_mul_f32 v[162:163], v[66:67], v[162:163]
	v_pk_mul_f32 v[166:167], v[56:57], v[166:167]
	v_pk_mul_f32 v[168:169], v[58:59], v[168:169]
	v_pk_mul_f32 v[160:161], v[160:161], v[60:61]
	v_pk_mul_f32 v[162:163], v[162:163], v[62:63]
	v_pk_mul_f32 v[166:167], v[166:167], v[52:53]
	v_pk_mul_f32 v[168:169], v[168:169], v[54:55]
	v_cvt_pk_bf16_f32 v60, v160, v161
	v_cvt_pk_bf16_f32 v61, v162, v163
	v_cvt_pk_bf16_f32 v62, v166, v167
	v_cvt_pk_bf16_f32 v63, v168, v169
	global_store_dwordx4 v[68:69], v[60:63], off nt
	v_lshl_add_u64 v[52:53], v[144:145], 1, v[154:155]
	v_pk_mul_f32 v[160:161], v[48:49], v[164:165] op_sel_hi:[1,0]
	v_pk_mul_f32 v[162:163], v[50:51], v[164:165] op_sel_hi:[1,0]
	v_pk_mul_f32 v[166:167], v[40:41], v[164:165] op_sel_hi:[1,0]
	v_pk_mul_f32 v[168:169], v[42:43], v[164:165] op_sel_hi:[1,0]
	v_exp_f32_e32 v160, v160
	v_exp_f32_e32 v161, v161
	v_exp_f32_e32 v162, v162
	v_exp_f32_e32 v163, v163
	v_exp_f32_e32 v166, v166
	v_exp_f32_e32 v167, v167
	v_exp_f32_e32 v168, v168
	v_exp_f32_e32 v169, v169
	v_pk_add_f32 v[160:161], v[160:161], 1.0 op_sel_hi:[1,0]
	v_pk_add_f32 v[162:163], v[162:163], 1.0 op_sel_hi:[1,0]
	v_pk_add_f32 v[166:167], v[166:167], 1.0 op_sel_hi:[1,0]
	v_pk_add_f32 v[168:169], v[168:169], 1.0 op_sel_hi:[1,0]
	v_rcp_f32_e32 v160, v160
	v_rcp_f32_e32 v161, v161
	v_rcp_f32_e32 v162, v162
	v_rcp_f32_e32 v163, v163
	v_rcp_f32_e32 v166, v166
	v_rcp_f32_e32 v167, v167
	v_rcp_f32_e32 v168, v168
	v_rcp_f32_e32 v169, v169
	v_pk_mul_f32 v[160:161], v[48:49], v[160:161]
	v_pk_mul_f32 v[162:163], v[50:51], v[162:163]
	v_pk_mul_f32 v[166:167], v[40:41], v[166:167]
	v_pk_mul_f32 v[168:169], v[42:43], v[168:169]
	v_pk_mul_f32 v[160:161], v[160:161], v[44:45]
	v_pk_mul_f32 v[162:163], v[162:163], v[46:47]
	v_pk_mul_f32 v[166:167], v[166:167], v[36:37]
	v_pk_mul_f32 v[168:169], v[168:169], v[38:39]
	v_cvt_pk_bf16_f32 v44, v160, v161
	v_cvt_pk_bf16_f32 v45, v162, v163
	v_cvt_pk_bf16_f32 v46, v166, v167
	v_cvt_pk_bf16_f32 v47, v168, v169
	global_store_dwordx4 v[52:53], v[44:47], off nt
	v_lshl_add_u64 v[36:37], v[146:147], 1, v[154:155]
	v_pk_mul_f32 v[160:161], v[32:33], v[164:165] op_sel_hi:[1,0]
	v_pk_mul_f32 v[162:163], v[34:35], v[164:165] op_sel_hi:[1,0]
	v_pk_mul_f32 v[166:167], v[24:25], v[164:165] op_sel_hi:[1,0]
	v_pk_mul_f32 v[168:169], v[26:27], v[164:165] op_sel_hi:[1,0]
	v_exp_f32_e32 v160, v160
	v_exp_f32_e32 v161, v161
	v_exp_f32_e32 v162, v162
	v_exp_f32_e32 v163, v163
	v_exp_f32_e32 v166, v166
	v_exp_f32_e32 v167, v167
	v_exp_f32_e32 v168, v168
	v_exp_f32_e32 v169, v169
	v_pk_add_f32 v[160:161], v[160:161], 1.0 op_sel_hi:[1,0]
	v_pk_add_f32 v[162:163], v[162:163], 1.0 op_sel_hi:[1,0]
	v_pk_add_f32 v[166:167], v[166:167], 1.0 op_sel_hi:[1,0]
	v_pk_add_f32 v[168:169], v[168:169], 1.0 op_sel_hi:[1,0]
	v_rcp_f32_e32 v160, v160
	v_rcp_f32_e32 v161, v161
	v_rcp_f32_e32 v162, v162
	v_rcp_f32_e32 v163, v163
	v_rcp_f32_e32 v166, v166
	v_rcp_f32_e32 v167, v167
	v_rcp_f32_e32 v168, v168
	v_rcp_f32_e32 v169, v169
	v_pk_mul_f32 v[160:161], v[32:33], v[160:161]
	v_pk_mul_f32 v[162:163], v[34:35], v[162:163]
	v_pk_mul_f32 v[166:167], v[24:25], v[166:167]
	v_pk_mul_f32 v[168:169], v[26:27], v[168:169]
	v_pk_mul_f32 v[160:161], v[160:161], v[28:29]
	v_pk_mul_f32 v[162:163], v[162:163], v[30:31]
	v_pk_mul_f32 v[166:167], v[166:167], v[20:21]
	v_pk_mul_f32 v[168:169], v[168:169], v[22:23]
	v_cvt_pk_bf16_f32 v28, v160, v161
	v_cvt_pk_bf16_f32 v29, v162, v163
	v_cvt_pk_bf16_f32 v30, v166, v167
	v_cvt_pk_bf16_f32 v31, v168, v169
	global_store_dwordx4 v[36:37], v[28:31], off nt
	v_lshl_add_u64 v[20:21], v[148:149], 1, v[154:155]
	v_pk_mul_f32 v[160:161], v[16:17], v[164:165] op_sel_hi:[1,0]
	v_pk_mul_f32 v[162:163], v[18:19], v[164:165] op_sel_hi:[1,0]
	v_pk_mul_f32 v[166:167], v[8:9], v[164:165] op_sel_hi:[1,0]
	v_pk_mul_f32 v[168:169], v[10:11], v[164:165] op_sel_hi:[1,0]
	v_exp_f32_e32 v160, v160
	v_exp_f32_e32 v161, v161
	v_exp_f32_e32 v162, v162
	v_exp_f32_e32 v163, v163
	v_exp_f32_e32 v166, v166
	v_exp_f32_e32 v167, v167
	v_exp_f32_e32 v168, v168
	v_exp_f32_e32 v169, v169
	v_pk_add_f32 v[160:161], v[160:161], 1.0 op_sel_hi:[1,0]
	v_pk_add_f32 v[162:163], v[162:163], 1.0 op_sel_hi:[1,0]
	v_pk_add_f32 v[166:167], v[166:167], 1.0 op_sel_hi:[1,0]
	v_pk_add_f32 v[168:169], v[168:169], 1.0 op_sel_hi:[1,0]
	v_rcp_f32_e32 v160, v160
	v_rcp_f32_e32 v161, v161
	v_rcp_f32_e32 v162, v162
	v_rcp_f32_e32 v163, v163
	v_rcp_f32_e32 v166, v166
	v_rcp_f32_e32 v167, v167
	v_rcp_f32_e32 v168, v168
	v_rcp_f32_e32 v169, v169
	v_pk_mul_f32 v[160:161], v[16:17], v[160:161]
	v_pk_mul_f32 v[162:163], v[18:19], v[162:163]
	v_pk_mul_f32 v[166:167], v[8:9], v[166:167]
	v_pk_mul_f32 v[168:169], v[10:11], v[168:169]
	v_pk_mul_f32 v[160:161], v[160:161], v[12:13]
	v_pk_mul_f32 v[162:163], v[162:163], v[14:15]
	v_pk_mul_f32 v[166:167], v[166:167], v[4:5]
	v_pk_mul_f32 v[168:169], v[168:169], v[6:7]
	v_cvt_pk_bf16_f32 v12, v160, v161
	v_cvt_pk_bf16_f32 v13, v162, v163
	v_cvt_pk_bf16_f32 v14, v166, v167
	v_cvt_pk_bf16_f32 v15, v168, v169
	global_store_dwordx4 v[20:21], v[12:15], off nt
	s_cbranch_vccnz .LBB0_156
	s_andn2_b64 vcc, exec, s[0:1]
	s_cbranch_vccnz .LBB0_155
	s_barrier
	s_branch .LBB0_155

.LBB0_747:
	v_mov_b32_e32 v164, 0xbfb8aa3b
	s_lshl_b32 s7, s44, 7
	s_or_b32 s7, s7, s38
	s_mul_i32 s16, s43, 0x2c0000
	s_mul_hi_i32 s11, s43, 0x2c0000
	s_add_u32 s18, s36, s16
	s_addc_u32 s11, s37, s11
	s_ashr_i32 s16, s7, 6
	s_ashr_i32 s17, s16, 31
	s_lshl_b64 s[16:17], s[16:17], 15
	s_add_u32 s16, s18, s16
	s_addc_u32 s17, s11, s17
	v_lshl_add_u64 v[154:155], s[16:17], 0, v[2:3]
	v_lshl_add_u64 v[156:157], v[140:141], 1, v[154:155]
	s_mov_b64 s[16:17], -1
	s_movk_i32 s45, 0x3000
	s_mov_b32 s47, 0x11000
	s_mov_b32 s48, 0x9000
	v_pk_mul_f32 v[160:161], v[128:129], v[164:165] op_sel_hi:[1,0]
	v_pk_mul_f32 v[162:163], v[130:131], v[164:165] op_sel_hi:[1,0]
	v_pk_mul_f32 v[166:167], v[120:121], v[164:165] op_sel_hi:[1,0]
	v_pk_mul_f32 v[168:169], v[122:123], v[164:165] op_sel_hi:[1,0]
	v_exp_f32_e32 v160, v160
	v_exp_f32_e32 v161, v161
	v_exp_f32_e32 v162, v162
	v_exp_f32_e32 v163, v163
	v_exp_f32_e32 v166, v166
	v_exp_f32_e32 v167, v167
	v_exp_f32_e32 v168, v168
	v_exp_f32_e32 v169, v169
	v_pk_add_f32 v[160:161], v[160:161], 1.0 op_sel_hi:[1,0]
	v_pk_add_f32 v[162:163], v[162:163], 1.0 op_sel_hi:[1,0]
	v_pk_add_f32 v[166:167], v[166:167], 1.0 op_sel_hi:[1,0]
	v_pk_add_f32 v[168:169], v[168:169], 1.0 op_sel_hi:[1,0]
	v_rcp_f32_e32 v160, v160
	v_rcp_f32_e32 v161, v161
	v_rcp_f32_e32 v162, v162
	v_rcp_f32_e32 v163, v163
	v_rcp_f32_e32 v166, v166
	v_rcp_f32_e32 v167, v167
	v_rcp_f32_e32 v168, v168
	v_rcp_f32_e32 v169, v169
	v_pk_mul_f32 v[160:161], v[128:129], v[160:161]
	v_pk_mul_f32 v[162:163], v[130:131], v[162:163]
	v_pk_mul_f32 v[166:167], v[120:121], v[166:167]
	v_pk_mul_f32 v[168:169], v[122:123], v[168:169]
	v_pk_mul_f32 v[160:161], v[160:161], v[124:125]
	v_pk_mul_f32 v[162:163], v[162:163], v[126:127]
	v_pk_mul_f32 v[166:167], v[166:167], v[116:117]
	v_pk_mul_f32 v[168:169], v[168:169], v[118:119]
	v_cvt_pk_bf16_f32 v124, v160, v161
	v_cvt_pk_bf16_f32 v125, v162, v163
	v_cvt_pk_bf16_f32 v126, v166, v167
	v_cvt_pk_bf16_f32 v127, v168, v169
	global_store_dwordx4 v[156:157], v[124:127], off nt
	v_pk_mul_f32 v[160:161], v[112:113], v[164:165] op_sel_hi:[1,0]
	v_pk_mul_f32 v[162:163], v[114:115], v[164:165] op_sel_hi:[1,0]
	v_pk_mul_f32 v[166:167], v[104:105], v[164:165] op_sel_hi:[1,0]
	v_pk_mul_f32 v[168:169], v[106:107], v[164:165] op_sel_hi:[1,0]
	v_exp_f32_e32 v160, v160
	v_exp_f32_e32 v161, v161
	v_exp_f32_e32 v162, v162
	v_exp_f32_e32 v163, v163
	v_exp_f32_e32 v166, v166
	v_exp_f32_e32 v167, v167
	v_exp_f32_e32 v168, v168
	v_exp_f32_e32 v169, v169
	v_pk_add_f32 v[160:161], v[160:161], 1.0 op_sel_hi:[1,0]
	v_pk_add_f32 v[162:163], v[162:163], 1.0 op_sel_hi:[1,0]
	v_pk_add_f32 v[166:167], v[166:167], 1.0 op_sel_hi:[1,0]
	v_pk_add_f32 v[168:169], v[168:169], 1.0 op_sel_hi:[1,0]
	v_rcp_f32_e32 v160, v160
	v_rcp_f32_e32 v161, v161
	v_rcp_f32_e32 v162, v162
	v_rcp_f32_e32 v163, v163
	v_rcp_f32_e32 v166, v166
	v_rcp_f32_e32 v167, v167
	v_rcp_f32_e32 v168, v168
	v_rcp_f32_e32 v169, v169
	v_pk_mul_f32 v[160:161], v[112:113], v[160:161]
	v_pk_mul_f32 v[162:163], v[114:115], v[162:163]
	v_pk_mul_f32 v[166:167], v[104:105], v[166:167]
	v_pk_mul_f32 v[168:169], v[106:107], v[168:169]
	v_pk_mul_f32 v[160:161], v[160:161], v[108:109]
	v_pk_mul_f32 v[162:163], v[162:163], v[110:111]
	v_pk_mul_f32 v[166:167], v[166:167], v[100:101]
	v_pk_mul_f32 v[168:169], v[168:169], v[102:103]
	v_cvt_pk_bf16_f32 v108, v160, v161
	v_cvt_pk_bf16_f32 v109, v162, v163
	v_cvt_pk_bf16_f32 v110, v166, v167
	v_cvt_pk_bf16_f32 v111, v168, v169
	global_store_dwordx4 v[156:157], v[108:111], off offset:2048 nt
	v_pk_mul_f32 v[160:161], v[96:97], v[164:165] op_sel_hi:[1,0]
	v_pk_mul_f32 v[162:163], v[98:99], v[164:165] op_sel_hi:[1,0]
	v_pk_mul_f32 v[166:167], v[88:89], v[164:165] op_sel_hi:[1,0]
	v_pk_mul_f32 v[168:169], v[90:91], v[164:165] op_sel_hi:[1,0]
	v_exp_f32_e32 v160, v160
	v_exp_f32_e32 v161, v161
	v_exp_f32_e32 v162, v162
	v_exp_f32_e32 v163, v163
	v_exp_f32_e32 v166, v166
	v_exp_f32_e32 v167, v167
	v_exp_f32_e32 v168, v168
	v_exp_f32_e32 v169, v169
	v_pk_add_f32 v[160:161], v[160:161], 1.0 op_sel_hi:[1,0]
	v_pk_add_f32 v[162:163], v[162:163], 1.0 op_sel_hi:[1,0]
	v_pk_add_f32 v[166:167], v[166:167], 1.0 op_sel_hi:[1,0]
	v_pk_add_f32 v[168:169], v[168:169], 1.0 op_sel_hi:[1,0]
	v_rcp_f32_e32 v160, v160
	v_rcp_f32_e32 v161, v161
	v_rcp_f32_e32 v162, v162
	v_rcp_f32_e32 v163, v163
	v_rcp_f32_e32 v166, v166
	v_rcp_f32_e32 v167, v167
	v_rcp_f32_e32 v168, v168
	v_rcp_f32_e32 v169, v169
	v_pk_mul_f32 v[160:161], v[96:97], v[160:161]
	v_pk_mul_f32 v[162:163], v[98:99], v[162:163]
	v_pk_mul_f32 v[166:167], v[88:89], v[166:167]
	v_pk_mul_f32 v[168:169], v[90:91], v[168:169]
	v_pk_mul_f32 v[160:161], v[160:161], v[92:93]
	v_pk_mul_f32 v[162:163], v[162:163], v[94:95]
	v_pk_mul_f32 v[166:167], v[166:167], v[84:85]
	v_pk_mul_f32 v[168:169], v[168:169], v[86:87]
	v_cvt_pk_bf16_f32 v92, v160, v161
	v_cvt_pk_bf16_f32 v93, v162, v163
	v_cvt_pk_bf16_f32 v94, v166, v167
	v_cvt_pk_bf16_f32 v95, v168, v169
	v_add_co_u32_e32 v84, vcc, s53, v156
	s_nop 1
	v_addc_co_u32_e32 v85, vcc, 0, v157, vcc
	global_store_dwordx4 v[84:85], v[92:95], off nt
	s_andn2_b64 vcc, exec, s[8:9]
	v_pk_mul_f32 v[160:161], v[80:81], v[164:165] op_sel_hi:[1,0]
	v_pk_mul_f32 v[162:163], v[82:83], v[164:165] op_sel_hi:[1,0]
	v_pk_mul_f32 v[166:167], v[72:73], v[164:165] op_sel_hi:[1,0]
	v_pk_mul_f32 v[168:169], v[74:75], v[164:165] op_sel_hi:[1,0]
	v_exp_f32_e32 v160, v160
	v_exp_f32_e32 v161, v161
	v_exp_f32_e32 v162, v162
	v_exp_f32_e32 v163, v163
	v_exp_f32_e32 v166, v166
	v_exp_f32_e32 v167, v167
	v_exp_f32_e32 v168, v168
	v_exp_f32_e32 v169, v169
	v_pk_add_f32 v[160:161], v[160:161], 1.0 op_sel_hi:[1,0]
	v_pk_add_f32 v[162:163], v[162:163], 1.0 op_sel_hi:[1,0]
	v_pk_add_f32 v[166:167], v[166:167], 1.0 op_sel_hi:[1,0]
	v_pk_add_f32 v[168:169], v[168:169], 1.0 op_sel_hi:[1,0]
	v_rcp_f32_e32 v160, v160
	v_rcp_f32_e32 v161, v161
	v_rcp_f32_e32 v162, v162
	v_rcp_f32_e32 v163, v163
	v_rcp_f32_e32 v166, v166
	v_rcp_f32_e32 v167, v167
	v_rcp_f32_e32 v168, v168
	v_rcp_f32_e32 v169, v169
	v_pk_mul_f32 v[160:161], v[80:81], v[160:161]
	v_pk_mul_f32 v[162:163], v[82:83], v[162:163]
	v_pk_mul_f32 v[166:167], v[72:73], v[166:167]
	v_pk_mul_f32 v[168:169], v[74:75], v[168:169]
	v_pk_mul_f32 v[160:161], v[160:161], v[76:77]
	v_pk_mul_f32 v[162:163], v[162:163], v[78:79]
	v_pk_mul_f32 v[166:167], v[166:167], v[68:69]
	v_pk_mul_f32 v[168:169], v[168:169], v[70:71]
	v_cvt_pk_bf16_f32 v76, v160, v161
	v_cvt_pk_bf16_f32 v77, v162, v163
	v_cvt_pk_bf16_f32 v78, v166, v167
	v_cvt_pk_bf16_f32 v79, v168, v169
	global_store_dwordx4 v[84:85], v[76:79], off offset:2048 nt
	v_lshl_add_u64 v[68:69], v[142:143], 1, v[154:155]
	v_pk_mul_f32 v[160:161], v[64:65], v[164:165] op_sel_hi:[1,0]
	v_pk_mul_f32 v[162:163], v[66:67], v[164:165] op_sel_hi:[1,0]
	v_pk_mul_f32 v[166:167], v[56:57], v[164:165] op_sel_hi:[1,0]
	v_pk_mul_f32 v[168:169], v[58:59], v[164:165] op_sel_hi:[1,0]
	v_exp_f32_e32 v160, v160
	v_exp_f32_e32 v161, v161
	v_exp_f32_e32 v162, v162
	v_exp_f32_e32 v163, v163
	v_exp_f32_e32 v166, v166
	v_exp_f32_e32 v167, v167
	v_exp_f32_e32 v168, v168
	v_exp_f32_e32 v169, v169
	v_pk_add_f32 v[160:161], v[160:161], 1.0 op_sel_hi:[1,0]
	v_pk_add_f32 v[162:163], v[162:163], 1.0 op_sel_hi:[1,0]
	v_pk_add_f32 v[166:167], v[166:167], 1.0 op_sel_hi:[1,0]
	v_pk_add_f32 v[168:169], v[168:169], 1.0 op_sel_hi:[1,0]
	v_rcp_f32_e32 v160, v160
	v_rcp_f32_e32 v161, v161
	v_rcp_f32_e32 v162, v162
	v_rcp_f32_e32 v163, v163
	v_rcp_f32_e32 v166, v166
	v_rcp_f32_e32 v167, v167
	v_rcp_f32_e32 v168, v168
	v_rcp_f32_e32 v169, v169
	v_pk_mul_f32 v[160:161], v[64:65], v[160:161]
	v_pk_mul_f32 v[162:163], v[66:67], v[162:163]
	v_pk_mul_f32 v[166:167], v[56:57], v[166:167]
	v_pk_mul_f32 v[168:169], v[58:59], v[168:169]
	v_pk_mul_f32 v[160:161], v[160:161], v[60:61]
	v_pk_mul_f32 v[162:163], v[162:163], v[62:63]
	v_pk_mul_f32 v[166:167], v[166:167], v[52:53]
	v_pk_mul_f32 v[168:169], v[168:169], v[54:55]
	v_cvt_pk_bf16_f32 v60, v160, v161
	v_cvt_pk_bf16_f32 v61, v162, v163
	v_cvt_pk_bf16_f32 v62, v166, v167
	v_cvt_pk_bf16_f32 v63, v168, v169
	global_store_dwordx4 v[68:69], v[60:63], off nt
	v_lshl_add_u64 v[52:53], v[144:145], 1, v[154:155]
	v_pk_mul_f32 v[160:161], v[48:49], v[164:165] op_sel_hi:[1,0]
	v_pk_mul_f32 v[162:163], v[50:51], v[164:165] op_sel_hi:[1,0]
	v_pk_mul_f32 v[166:167], v[40:41], v[164:165] op_sel_hi:[1,0]
	v_pk_mul_f32 v[168:169], v[42:43], v[164:165] op_sel_hi:[1,0]
	v_exp_f32_e32 v160, v160
	v_exp_f32_e32 v161, v161
	v_exp_f32_e32 v162, v162
	v_exp_f32_e32 v163, v163
	v_exp_f32_e32 v166, v166
	v_exp_f32_e32 v167, v167
	v_exp_f32_e32 v168, v168
	v_exp_f32_e32 v169, v169
	v_pk_add_f32 v[160:161], v[160:161], 1.0 op_sel_hi:[1,0]
	v_pk_add_f32 v[162:163], v[162:163], 1.0 op_sel_hi:[1,0]
	v_pk_add_f32 v[166:167], v[166:167], 1.0 op_sel_hi:[1,0]
	v_pk_add_f32 v[168:169], v[168:169], 1.0 op_sel_hi:[1,0]
	v_rcp_f32_e32 v160, v160
	v_rcp_f32_e32 v161, v161
	v_rcp_f32_e32 v162, v162
	v_rcp_f32_e32 v163, v163
	v_rcp_f32_e32 v166, v166
	v_rcp_f32_e32 v167, v167
	v_rcp_f32_e32 v168, v168
	v_rcp_f32_e32 v169, v169
	v_pk_mul_f32 v[160:161], v[48:49], v[160:161]
	v_pk_mul_f32 v[162:163], v[50:51], v[162:163]
	v_pk_mul_f32 v[166:167], v[40:41], v[166:167]
	v_pk_mul_f32 v[168:169], v[42:43], v[168:169]
	v_pk_mul_f32 v[160:161], v[160:161], v[44:45]
	v_pk_mul_f32 v[162:163], v[162:163], v[46:47]
	v_pk_mul_f32 v[166:167], v[166:167], v[36:37]
	v_pk_mul_f32 v[168:169], v[168:169], v[38:39]
	v_cvt_pk_bf16_f32 v44, v160, v161
	v_cvt_pk_bf16_f32 v45, v162, v163
	v_cvt_pk_bf16_f32 v46, v166, v167
	v_cvt_pk_bf16_f32 v47, v168, v169
	global_store_dwordx4 v[52:53], v[44:47], off nt
	v_lshl_add_u64 v[36:37], v[146:147], 1, v[154:155]
	v_pk_mul_f32 v[160:161], v[32:33], v[164:165] op_sel_hi:[1,0]
	v_pk_mul_f32 v[162:163], v[34:35], v[164:165] op_sel_hi:[1,0]
	v_pk_mul_f32 v[166:167], v[24:25], v[164:165] op_sel_hi:[1,0]
	v_pk_mul_f32 v[168:169], v[26:27], v[164:165] op_sel_hi:[1,0]
	v_exp_f32_e32 v160, v160
	v_exp_f32_e32 v161, v161
	v_exp_f32_e32 v162, v162
	v_exp_f32_e32 v163, v163
	v_exp_f32_e32 v166, v166
	v_exp_f32_e32 v167, v167
	v_exp_f32_e32 v168, v168
	v_exp_f32_e32 v169, v169
	v_pk_add_f32 v[160:161], v[160:161], 1.0 op_sel_hi:[1,0]
	v_pk_add_f32 v[162:163], v[162:163], 1.0 op_sel_hi:[1,0]
	v_pk_add_f32 v[166:167], v[166:167], 1.0 op_sel_hi:[1,0]
	v_pk_add_f32 v[168:169], v[168:169], 1.0 op_sel_hi:[1,0]
	v_rcp_f32_e32 v160, v160
	v_rcp_f32_e32 v161, v161
	v_rcp_f32_e32 v162, v162
	v_rcp_f32_e32 v163, v163
	v_rcp_f32_e32 v166, v166
	v_rcp_f32_e32 v167, v167
	v_rcp_f32_e32 v168, v168
	v_rcp_f32_e32 v169, v169
	v_pk_mul_f32 v[160:161], v[32:33], v[160:161]
	v_pk_mul_f32 v[162:163], v[34:35], v[162:163]
	v_pk_mul_f32 v[166:167], v[24:25], v[166:167]
	v_pk_mul_f32 v[168:169], v[26:27], v[168:169]
	v_pk_mul_f32 v[160:161], v[160:161], v[28:29]
	v_pk_mul_f32 v[162:163], v[162:163], v[30:31]
	v_pk_mul_f32 v[166:167], v[166:167], v[20:21]
	v_pk_mul_f32 v[168:169], v[168:169], v[22:23]
	v_cvt_pk_bf16_f32 v28, v160, v161
	v_cvt_pk_bf16_f32 v29, v162, v163
	v_cvt_pk_bf16_f32 v30, v166, v167
	v_cvt_pk_bf16_f32 v31, v168, v169
	global_store_dwordx4 v[36:37], v[28:31], off nt
	v_lshl_add_u64 v[20:21], v[148:149], 1, v[154:155]
	v_pk_mul_f32 v[160:161], v[16:17], v[164:165] op_sel_hi:[1,0]
	v_pk_mul_f32 v[162:163], v[18:19], v[164:165] op_sel_hi:[1,0]
	v_pk_mul_f32 v[166:167], v[8:9], v[164:165] op_sel_hi:[1,0]
	v_pk_mul_f32 v[168:169], v[10:11], v[164:165] op_sel_hi:[1,0]
	v_exp_f32_e32 v160, v160
	v_exp_f32_e32 v161, v161
	v_exp_f32_e32 v162, v162
	v_exp_f32_e32 v163, v163
	v_exp_f32_e32 v166, v166
	v_exp_f32_e32 v167, v167
	v_exp_f32_e32 v168, v168
	v_exp_f32_e32 v169, v169
	v_pk_add_f32 v[160:161], v[160:161], 1.0 op_sel_hi:[1,0]
	v_pk_add_f32 v[162:163], v[162:163], 1.0 op_sel_hi:[1,0]
	v_pk_add_f32 v[166:167], v[166:167], 1.0 op_sel_hi:[1,0]
	v_pk_add_f32 v[168:169], v[168:169], 1.0 op_sel_hi:[1,0]
	v_rcp_f32_e32 v160, v160
	v_rcp_f32_e32 v161, v161
	v_rcp_f32_e32 v162, v162
	v_rcp_f32_e32 v163, v163
	v_rcp_f32_e32 v166, v166
	v_rcp_f32_e32 v167, v167
	v_rcp_f32_e32 v168, v168
	v_rcp_f32_e32 v169, v169
	v_pk_mul_f32 v[160:161], v[16:17], v[160:161]
	v_pk_mul_f32 v[162:163], v[18:19], v[162:163]
	v_pk_mul_f32 v[166:167], v[8:9], v[166:167]
	v_pk_mul_f32 v[168:169], v[10:11], v[168:169]
	v_pk_mul_f32 v[160:161], v[160:161], v[12:13]
	v_pk_mul_f32 v[162:163], v[162:163], v[14:15]
	v_pk_mul_f32 v[166:167], v[166:167], v[4:5]
	v_pk_mul_f32 v[168:169], v[168:169], v[6:7]
	v_cvt_pk_bf16_f32 v12, v160, v161
	v_cvt_pk_bf16_f32 v13, v162, v163
	v_cvt_pk_bf16_f32 v14, v166, v167
	v_cvt_pk_bf16_f32 v15, v168, v169
	global_store_dwordx4 v[20:21], v[12:15], off nt
	s_cbranch_vccnz .LBB0_740
	s_andn2_b64 vcc, exec, s[0:1]
	s_cbranch_vccnz .LBB0_739
	s_barrier
	s_branch .LBB0_739
